# adds norm-phase output ladder de-serialization: per row the gamma/scale/shift loads of chunks 1-3 hoisted next to chunk 0's (12 loads in flight, counted vmcnt) instead of load-wait-compute-store per c
# baseline (speedup 1.0000x reference)
.LBB0_475:
	s_or_b64 exec, exec, s[36:37]
	s_waitcnt vmcnt(0)
	v_mul_f32_e32 v0, v63, v63
	v_mul_f32_e32 v67, v51, v51
	v_fmac_f32_e32 v0, v62, v62
	v_fmac_f32_e32 v67, v50, v50
	v_fmac_f32_e32 v0, v64, v64
	v_fmac_f32_e32 v67, v52, v52
	v_fmac_f32_e32 v0, v65, v65
	v_fmac_f32_e32 v67, v53, v53
	v_add_f32_e32 v0, v67, v0
	v_mul_f32_e32 v67, v47, v47
	v_fmac_f32_e32 v67, v46, v46
	v_fmac_f32_e32 v67, v48, v48
	v_fmac_f32_e32 v67, v49, v49
	v_add_f32_e32 v0, v67, v0
	v_mul_f32_e32 v67, v31, v31
	v_fmac_f32_e32 v67, v30, v30
	v_fmac_f32_e32 v67, v32, v32
	v_fmac_f32_e32 v67, v33, v33
	v_add_f32_e32 v0, v67, v0
	v_min_i32_e32 v67, 0x8000, v66
	v_ashrrev_i32_e32 v67, 12, v67
	v_mul_i32_i24_e32 v98, 0x1800, v67
	v_ashrrev_i32_e32 v99, 31, v98
	v_lshl_add_u64 v[100:101], v[98:99], 2, s[22:23]
	s_mov_b64 s[10:11], 0x1000
	v_lshl_add_u64 v[98:99], v[100:101], 0, s[10:11]
	v_mov_b32_e32 v85, v1
	v_lshl_add_u64 v[106:107], v[98:99], 0, v[84:85]
	global_load_dwordx4 v[102:105], v[76:77], off
	global_load_dwordx4 v[114:117], v[106:107], off
	v_lshl_add_u64 v[100:101], v[100:101], 0, v[84:85]
	global_load_dwordx4 v[118:121], v[100:101], off
	v_mov_b32_e32 v87, v1
	v_mov_b32_e32 v89, v1
	v_mov_b32_e32 v91, v1
	global_load_dwordx4 v[168:171], v[76:77], off offset:1024
	v_lshl_add_u64 v[172:173], v[98:99], 0, v[86:87]
	global_load_dwordx4 v[172:175], v[172:173], off
	global_load_dwordx4 v[176:179], v[100:101], off offset:1024
	global_load_dwordx4 v[180:183], v[76:77], off offset:2048
	v_lshl_add_u64 v[184:185], v[98:99], 0, v[88:89]
	global_load_dwordx4 v[184:187], v[184:185], off
	global_load_dwordx4 v[188:191], v[100:101], off offset:2048
	global_load_dwordx4 v[192:195], v[76:77], off offset:3072
	v_lshl_add_u64 v[196:197], v[98:99], 0, v[90:91]
	global_load_dwordx4 v[196:199], v[196:197], off
	global_load_dwordx4 v[200:203], v[100:101], off offset:3072
	ds_bpermute_b32 v67, v108, v0
	v_mov_b32_e32 v87, v1
	v_mov_b32_e32 v89, v1
	v_mov_b32_e32 v91, v1
	s_waitcnt lgkmcnt(0)
	v_add_f32_e32 v0, v0, v67
	ds_bpermute_b32 v67, v109, v0
	s_waitcnt lgkmcnt(0)
	v_add_f32_e32 v0, v0, v67
	ds_bpermute_b32 v67, v110, v0
	s_waitcnt lgkmcnt(0)
	v_add_f32_e32 v0, v0, v67
	ds_bpermute_b32 v67, v111, v0
	s_waitcnt lgkmcnt(0)
	v_add_f32_e32 v0, v0, v67
	ds_bpermute_b32 v67, v112, v0
	s_waitcnt lgkmcnt(0)
	v_add_f32_e32 v0, v0, v67
	ds_bpermute_b32 v67, v113, v0
	s_waitcnt lgkmcnt(0)
	v_add_f32_e32 v0, v0, v67
	v_fmamk_f32 v0, v0, 0x3a800000, v218
	v_cmp_gt_f32_e32 vcc, s13, v0
	v_mul_f32_e32 v67, 0x4b800000, v0
	s_nop 0
	v_cndmask_b32_e32 v0, v0, v67, vcc
	v_rsq_f32_e32 v0, v0
	s_nop 0
	v_mul_f32_e32 v67, 0x45800000, v0
	v_cndmask_b32_e32 v0, v0, v67, vcc
	v_pk_mul_f32 v[64:65], v[64:65], v[0:1] op_sel_hi:[1,0]
	v_pk_mul_f32 v[62:63], v[62:63], v[0:1] op_sel_hi:[1,0]
	v_pk_mul_f32 v[52:53], v[52:53], v[0:1] op_sel_hi:[1,0]
	v_pk_mul_f32 v[50:51], v[50:51], v[0:1] op_sel_hi:[1,0]
	v_pk_mul_f32 v[48:49], v[48:49], v[0:1] op_sel_hi:[1,0]
	v_pk_mul_f32 v[46:47], v[46:47], v[0:1] op_sel_hi:[1,0]
	v_pk_mul_f32 v[32:33], v[32:33], v[0:1] op_sel_hi:[1,0]
	v_pk_mul_f32 v[30:31], v[30:31], v[0:1] op_sel_hi:[1,0]
	v_cmp_gt_i32_e32 vcc, s4, v96
	s_waitcnt vmcnt(11)
	v_pk_mul_f32 v[62:63], v[102:103], v[62:63]
	v_pk_mul_f32 v[64:65], v[104:105], v[64:65]
	s_waitcnt vmcnt(10)
	v_pk_add_f32 v[102:103], v[116:117], 1.0 op_sel_hi:[1,0]
	v_pk_add_f32 v[104:105], v[114:115], 1.0 op_sel_hi:[1,0]
	s_waitcnt vmcnt(9)
	v_pk_fma_f32 v[64:65], v[102:103], v[64:65], v[120:121]
	v_pk_fma_f32 v[62:63], v[104:105], v[62:63], v[118:119]
	v_lshl_add_u64 v[102:103], v[98:99], 0, v[86:87]
	v_cvt_pk_bf16_f32 v62, v62, v63
	v_cvt_pk_bf16_f32 v63, v64, v65
	global_store_dwordx2 v[82:83], v[62:63], off
	s_waitcnt vmcnt(7)
	v_pk_mul_f32 v[50:51], v[168:169], v[50:51]
	v_pk_mul_f32 v[52:53], v[170:171], v[52:53]
	v_pk_add_f32 v[62:63], v[174:175], 1.0 op_sel_hi:[1, 0]
	v_pk_add_f32 v[64:65], v[172:173], 1.0 op_sel_hi:[1, 0]
	v_pk_fma_f32 v[52:53], v[62:63], v[52:53], v[178:179]
	v_pk_fma_f32 v[50:51], v[64:65], v[50:51], v[176:177]
	v_lshl_add_u64 v[62:63], v[98:99], 0, v[88:89]
	v_cvt_pk_bf16_f32 v50, v50, v51
	v_cvt_pk_bf16_f32 v51, v52, v53
	global_store_dwordx2 v[82:83], v[50:51], off offset:512
	s_waitcnt vmcnt(5)
	v_pk_mul_f32 v[46:47], v[180:181], v[46:47]
	v_pk_mul_f32 v[48:49], v[182:183], v[48:49]
	v_pk_add_f32 v[50:51], v[186:187], 1.0 op_sel_hi:[1, 0]
	v_pk_add_f32 v[52:53], v[184:185], 1.0 op_sel_hi:[1, 0]
	v_pk_fma_f32 v[48:49], v[50:51], v[48:49], v[190:191]
	v_pk_fma_f32 v[46:47], v[52:53], v[46:47], v[188:189]
	v_lshl_add_u64 v[50:51], v[98:99], 0, v[90:91]
	v_cvt_pk_bf16_f32 v46, v46, v47
	v_cvt_pk_bf16_f32 v47, v48, v49
	global_store_dwordx2 v[82:83], v[46:47], off offset:1024
	s_waitcnt vmcnt(3)
	v_pk_mul_f32 v[30:31], v[30:31], v[192:193]
	v_pk_mul_f32 v[32:33], v[32:33], v[194:195]
	v_pk_add_f32 v[46:47], v[198:199], 1.0 op_sel_hi:[1, 0]
	v_pk_add_f32 v[48:49], v[196:197], 1.0 op_sel_hi:[1, 0]
	v_pk_fma_f32 v[32:33], v[32:33], v[46:47], v[202:203]
	v_pk_fma_f32 v[30:31], v[30:31], v[48:49], v[200:201]
	s_nop 0
	v_cvt_pk_bf16_f32 v30, v30, v31
	v_cvt_pk_bf16_f32 v31, v32, v33
	global_store_dwordx2 v[82:83], v[30:31], off offset:1536
	s_and_saveexec_b64 s[36:37], vcc
	s_cbranch_execz .LBB0_478
	v_mul_f32_e32 v0, v59, v59
	v_mul_f32_e32 v30, v43, v43
	v_fmac_f32_e32 v0, v58, v58
	v_fmac_f32_e32 v30, v42, v42
	v_fmac_f32_e32 v0, v60, v60
	v_fmac_f32_e32 v30, v44, v44
	v_fmac_f32_e32 v0, v61, v61
	v_fmac_f32_e32 v30, v45, v45
	v_add_f32_e32 v0, v30, v0
	v_mul_f32_e32 v30, v39, v39
	v_fmac_f32_e32 v30, v38, v38
	v_fmac_f32_e32 v30, v40, v40
	v_fmac_f32_e32 v30, v41, v41
	v_add_f32_e32 v0, v30, v0
	v_mul_f32_e32 v30, v35, v35
	v_fmac_f32_e32 v30, v34, v34
	v_fmac_f32_e32 v30, v36, v36
	v_fmac_f32_e32 v30, v37, v37
	v_add_f32_e32 v0, v30, v0
	ds_bpermute_b32 v46, v108, v0
	v_min_i32_e32 v30, 0x8000, v96
	v_ashrrev_i32_e32 v30, 12, v30
	v_mul_i32_i24_e32 v30, 0x1800, v30
	v_ashrrev_i32_e32 v31, 31, v30
	s_waitcnt lgkmcnt(0)
	v_add_f32_e32 v0, v0, v46
	ds_bpermute_b32 v46, v109, v0
	v_lshl_add_u64 v[32:33], v[30:31], 2, s[22:23]
	v_lshl_add_u64 v[30:31], v[32:33], 0, s[10:11]
	v_lshl_add_u64 v[52:53], v[30:31], 0, v[84:85]
	v_ashrrev_i32_e32 v97, 31, v96
	s_waitcnt lgkmcnt(0)
	v_add_f32_e32 v0, v0, v46
	ds_bpermute_b32 v46, v110, v0
	global_load_dwordx4 v[48:51], v[76:77], off
	global_load_dwordx4 v[62:65], v[52:53], off
	v_lshl_add_u64 v[32:33], v[32:33], 0, v[84:85]
	s_waitcnt lgkmcnt(0)
	v_add_f32_e32 v0, v0, v46
	ds_bpermute_b32 v46, v111, v0
	s_waitcnt lgkmcnt(0)
	v_add_f32_e32 v0, v0, v46
	ds_bpermute_b32 v46, v112, v0
	s_waitcnt lgkmcnt(0)
	v_add_f32_e32 v0, v0, v46
	ds_bpermute_b32 v46, v113, v0
	s_waitcnt lgkmcnt(0)
	v_add_f32_e32 v0, v0, v46
	v_fmamk_f32 v0, v0, 0x3a800000, v218
	v_cmp_gt_f32_e32 vcc, s13, v0
	v_mul_f32_e32 v46, 0x4b800000, v0
	s_nop 0
	v_cndmask_b32_e32 v0, v0, v46, vcc
	v_rsq_f32_e32 v0, v0
	s_nop 0
	v_mul_f32_e32 v46, 0x45800000, v0
	v_cndmask_b32_e32 v0, v0, v46, vcc
	v_lshlrev_b64 v[46:47], 11, v[96:97]
	global_load_dwordx4 v[96:99], v[32:33], off
	v_mov_b32_e32 v87, v1
	v_mov_b32_e32 v89, v1
	v_mov_b32_e32 v91, v1
	global_load_dwordx4 v[168:171], v[76:77], off offset:1024
	v_lshl_add_u64 v[172:173], v[30:31], 0, v[86:87]
	global_load_dwordx4 v[172:175], v[172:173], off
	global_load_dwordx4 v[176:179], v[32:33], off offset:1024
	global_load_dwordx4 v[180:183], v[76:77], off offset:2048
	v_lshl_add_u64 v[184:185], v[30:31], 0, v[88:89]
	global_load_dwordx4 v[184:187], v[184:185], off
	global_load_dwordx4 v[188:191], v[32:33], off offset:2048
	global_load_dwordx4 v[192:195], v[76:77], off offset:3072
	v_lshl_add_u64 v[196:197], v[30:31], 0, v[90:91]
	global_load_dwordx4 v[196:199], v[196:197], off
	global_load_dwordx4 v[200:203], v[32:33], off offset:3072
	v_pk_mul_f32 v[52:53], v[60:61], v[0:1] op_sel_hi:[1,0]
	v_pk_mul_f32 v[58:59], v[58:59], v[0:1] op_sel_hi:[1,0]
	v_pk_mul_f32 v[44:45], v[44:45], v[0:1] op_sel_hi:[1,0]
	v_pk_mul_f32 v[42:43], v[42:43], v[0:1] op_sel_hi:[1,0]
	v_pk_mul_f32 v[40:41], v[40:41], v[0:1] op_sel_hi:[1,0]
	v_pk_mul_f32 v[38:39], v[38:39], v[0:1] op_sel_hi:[1,0]
	v_pk_mul_f32 v[36:37], v[36:37], v[0:1] op_sel_hi:[1,0]
	v_pk_mul_f32 v[34:35], v[34:35], v[0:1] op_sel_hi:[1,0]
	s_waitcnt vmcnt(11)
	v_pk_mul_f32 v[48:49], v[48:49], v[58:59]
	v_pk_mul_f32 v[50:51], v[50:51], v[52:53]
	s_waitcnt vmcnt(10)
	v_pk_add_f32 v[52:53], v[64:65], 1.0 op_sel_hi:[1,0]
	v_pk_add_f32 v[58:59], v[62:63], 1.0 op_sel_hi:[1,0]
	v_lshl_add_u64 v[62:63], v[80:81], 0, v[46:47]
	s_waitcnt vmcnt(9)
	v_pk_fma_f32 v[50:51], v[52:53], v[50:51], v[98:99]
	v_pk_fma_f32 v[48:49], v[58:59], v[48:49], v[96:97]
	s_nop 0
	v_cvt_pk_bf16_f32 v48, v48, v49
	v_cvt_pk_bf16_f32 v49, v50, v51
	global_store_dwordx2 v[62:63], v[48:49], off
	v_lshl_add_u64 v[50:51], v[30:31], 0, v[86:87]
	s_waitcnt vmcnt(7)
	v_pk_mul_f32 v[42:43], v[168:169], v[42:43]
	v_pk_mul_f32 v[44:45], v[170:171], v[44:45]
	v_pk_add_f32 v[46:47], v[174:175], 1.0 op_sel_hi:[1, 0]
	v_pk_add_f32 v[48:49], v[172:173], 1.0 op_sel_hi:[1, 0]
	v_pk_fma_f32 v[44:45], v[46:47], v[44:45], v[178:179]
	v_pk_fma_f32 v[42:43], v[48:49], v[42:43], v[176:177]
	v_lshl_add_u64 v[46:47], v[30:31], 0, v[88:89]
	v_cvt_pk_bf16_f32 v42, v42, v43
	v_cvt_pk_bf16_f32 v43, v44, v45
	global_store_dwordx2 v[62:63], v[42:43], off offset:512
	v_lshl_add_u64 v[30:31], v[30:31], 0, v[90:91]
	s_waitcnt vmcnt(5)
	v_pk_mul_f32 v[38:39], v[180:181], v[38:39]
	v_pk_mul_f32 v[40:41], v[182:183], v[40:41]
	v_pk_add_f32 v[42:43], v[186:187], 1.0 op_sel_hi:[1, 0]
	v_pk_add_f32 v[44:45], v[184:185], 1.0 op_sel_hi:[1, 0]
	v_pk_fma_f32 v[40:41], v[42:43], v[40:41], v[190:191]
	v_pk_fma_f32 v[38:39], v[44:45], v[38:39], v[188:189]
	s_nop 0
	v_cvt_pk_bf16_f32 v38, v38, v39
	v_cvt_pk_bf16_f32 v39, v40, v41
	global_store_dwordx2 v[62:63], v[38:39], off offset:1024
	s_waitcnt vmcnt(3)
	v_pk_mul_f32 v[34:35], v[34:35], v[192:193]
	v_pk_mul_f32 v[36:37], v[36:37], v[194:195]
	v_pk_add_f32 v[38:39], v[198:199], 1.0 op_sel_hi:[1, 0]
	v_pk_add_f32 v[40:41], v[196:197], 1.0 op_sel_hi:[1, 0]
	v_pk_fma_f32 v[32:33], v[36:37], v[38:39], v[202:203]
	v_pk_fma_f32 v[30:31], v[34:35], v[40:41], v[200:201]
	s_nop 0
	v_cvt_pk_bf16_f32 v30, v30, v31
	v_cvt_pk_bf16_f32 v31, v32, v33
	global_store_dwordx2 v[62:63], v[30:31], off offset:1536
	s_or_b64 exec, exec, s[36:37]
	v_cmp_gt_i32_e32 vcc, s4, v94
	s_and_saveexec_b64 s[36:37], vcc
	s_cbranch_execnz .LBB0_479

.LBB0_479:
	v_mul_f32_e32 v0, v55, v55
	v_mul_f32_e32 v30, v27, v27
	v_fmac_f32_e32 v0, v54, v54
	v_fmac_f32_e32 v30, v26, v26
	v_fmac_f32_e32 v0, v56, v56
	v_fmac_f32_e32 v30, v28, v28
	v_fmac_f32_e32 v0, v57, v57
	v_fmac_f32_e32 v30, v29, v29
	v_add_f32_e32 v0, v30, v0
	v_mul_f32_e32 v30, v19, v19
	v_fmac_f32_e32 v30, v18, v18
	v_fmac_f32_e32 v30, v20, v20
	v_fmac_f32_e32 v30, v21, v21
	v_add_f32_e32 v0, v30, v0
	v_mul_f32_e32 v30, v15, v15
	v_fmac_f32_e32 v30, v14, v14
	v_fmac_f32_e32 v30, v16, v16
	v_fmac_f32_e32 v30, v17, v17
	v_add_f32_e32 v0, v30, v0
	v_min_i32_e32 v30, 0x8000, v94
	v_ashrrev_i32_e32 v30, 12, v30
	v_mul_i32_i24_e32 v30, 0x1800, v30
	v_ashrrev_i32_e32 v31, 31, v30
	v_lshl_add_u64 v[36:37], v[30:31], 2, s[22:23]
	ds_bpermute_b32 v30, v108, v0
	v_lshl_add_u64 v[34:35], v[36:37], 0, s[10:11]
	v_mov_b32_e32 v85, v1
	v_lshl_add_u64 v[38:39], v[34:35], 0, v[84:85]
	global_load_dwordx4 v[40:43], v[38:39], off
	s_waitcnt lgkmcnt(0)
	v_add_f32_e32 v0, v0, v30
	ds_bpermute_b32 v30, v109, v0
	v_lshl_add_u64 v[38:39], v[36:37], 0, v[84:85]
	global_load_dwordx4 v[44:47], v[38:39], off
	v_ashrrev_i32_e32 v95, 31, v94
	v_lshlrev_b64 v[48:49], 11, v[94:95]
	s_waitcnt lgkmcnt(0)
	v_add_f32_e32 v0, v0, v30
	ds_bpermute_b32 v30, v110, v0
	v_mov_b32_e32 v87, v1
	v_mov_b32_e32 v89, v1
	v_mov_b32_e32 v91, v1
	s_waitcnt lgkmcnt(0)
	v_add_f32_e32 v0, v0, v30
	ds_bpermute_b32 v30, v111, v0
	s_waitcnt lgkmcnt(0)
	v_add_f32_e32 v0, v0, v30
	ds_bpermute_b32 v30, v112, v0
	s_waitcnt lgkmcnt(0)
	v_add_f32_e32 v0, v0, v30
	ds_bpermute_b32 v30, v113, v0
	s_waitcnt lgkmcnt(0)
	v_add_f32_e32 v0, v0, v30
	v_fmamk_f32 v0, v0, 0x3a800000, v218
	v_cmp_gt_f32_e32 vcc, s13, v0
	v_mul_f32_e32 v30, 0x4b800000, v0
	s_waitcnt vmcnt(1)
	v_pk_add_f32 v[40:41], v[40:41], 1.0 op_sel_hi:[1,0]
	v_cndmask_b32_e32 v0, v0, v30, vcc
	v_rsq_f32_e32 v0, v0
	s_nop 0
	v_mul_f32_e32 v30, 0x45800000, v0
	v_cndmask_b32_e32 v0, v0, v30, vcc
	global_load_dwordx4 v[30:33], v[76:77], off
	v_mov_b32_e32 v87, v1
	v_mov_b32_e32 v89, v1
	v_mov_b32_e32 v91, v1
	global_load_dwordx4 v[168:171], v[76:77], off offset:1024
	v_lshl_add_u64 v[172:173], v[34:35], 0, v[86:87]
	global_load_dwordx4 v[172:175], v[172:173], off
	global_load_dwordx4 v[176:179], v[38:39], off offset:1024
	global_load_dwordx4 v[180:183], v[76:77], off offset:2048
	v_lshl_add_u64 v[184:185], v[34:35], 0, v[88:89]
	global_load_dwordx4 v[184:187], v[184:185], off
	global_load_dwordx4 v[188:191], v[38:39], off offset:2048
	global_load_dwordx4 v[192:195], v[76:77], off offset:3072
	v_lshl_add_u64 v[196:197], v[34:35], 0, v[90:91]
	global_load_dwordx4 v[196:199], v[196:197], off
	global_load_dwordx4 v[200:203], v[38:39], off offset:3072
	v_pk_mul_f32 v[36:37], v[56:57], v[0:1] op_sel_hi:[1,0]
	v_pk_mul_f32 v[50:51], v[54:55], v[0:1] op_sel_hi:[1,0]
	v_pk_mul_f32 v[28:29], v[28:29], v[0:1] op_sel_hi:[1,0]
	v_pk_mul_f32 v[26:27], v[26:27], v[0:1] op_sel_hi:[1,0]
	v_pk_mul_f32 v[20:21], v[20:21], v[0:1] op_sel_hi:[1,0]
	v_pk_mul_f32 v[18:19], v[18:19], v[0:1] op_sel_hi:[1,0]
	v_pk_mul_f32 v[16:17], v[16:17], v[0:1] op_sel_hi:[1,0]
	v_pk_mul_f32 v[14:15], v[14:15], v[0:1] op_sel_hi:[1,0]
	s_waitcnt vmcnt(9)
	v_pk_mul_f32 v[30:31], v[30:31], v[50:51]
	v_pk_mul_f32 v[32:33], v[32:33], v[36:37]
	v_pk_add_f32 v[36:37], v[42:43], 1.0 op_sel_hi:[1,0]
	v_pk_fma_f32 v[30:31], v[40:41], v[30:31], v[44:45]
	v_pk_fma_f32 v[32:33], v[36:37], v[32:33], v[46:47]
	v_cvt_pk_bf16_f32 v30, v30, v31
	v_cvt_pk_bf16_f32 v31, v32, v33
	v_lshl_add_u64 v[36:37], v[80:81], 0, v[48:49]
	global_store_dwordx2 v[36:37], v[30:31], off
	v_lshl_add_u64 v[40:41], v[34:35], 0, v[86:87]
	s_waitcnt vmcnt(7)
	v_pk_mul_f32 v[26:27], v[168:169], v[26:27]
	v_pk_mul_f32 v[28:29], v[170:171], v[28:29]
	v_pk_add_f32 v[30:31], v[174:175], 1.0 op_sel_hi:[1, 0]
	v_pk_add_f32 v[32:33], v[172:173], 1.0 op_sel_hi:[1, 0]
	v_pk_fma_f32 v[28:29], v[30:31], v[28:29], v[178:179]
	v_pk_fma_f32 v[26:27], v[32:33], v[26:27], v[176:177]
	v_lshl_add_u64 v[30:31], v[34:35], 0, v[88:89]
	v_cvt_pk_bf16_f32 v26, v26, v27
	v_cvt_pk_bf16_f32 v27, v28, v29
	global_store_dwordx2 v[36:37], v[26:27], off offset:512
	s_waitcnt vmcnt(5)
	v_pk_mul_f32 v[18:19], v[180:181], v[18:19]
	v_pk_mul_f32 v[20:21], v[182:183], v[20:21]
	v_pk_add_f32 v[26:27], v[186:187], 1.0 op_sel_hi:[1, 0]
	v_pk_add_f32 v[28:29], v[184:185], 1.0 op_sel_hi:[1, 0]
	v_pk_fma_f32 v[20:21], v[26:27], v[20:21], v[190:191]
	v_pk_fma_f32 v[18:19], v[28:29], v[18:19], v[188:189]
	v_lshl_add_u64 v[26:27], v[34:35], 0, v[90:91]
	v_cvt_pk_bf16_f32 v18, v18, v19
	v_cvt_pk_bf16_f32 v19, v20, v21
	global_store_dwordx2 v[36:37], v[18:19], off offset:1024
	s_waitcnt vmcnt(3)
	v_pk_mul_f32 v[14:15], v[14:15], v[192:193]
	v_pk_mul_f32 v[16:17], v[16:17], v[194:195]
	v_pk_add_f32 v[18:19], v[198:199], 1.0 op_sel_hi:[1, 0]
	v_pk_add_f32 v[20:21], v[196:197], 1.0 op_sel_hi:[1, 0]
	v_pk_fma_f32 v[16:17], v[16:17], v[18:19], v[202:203]
	v_pk_fma_f32 v[14:15], v[14:15], v[20:21], v[200:201]
	s_nop 0
	v_cvt_pk_bf16_f32 v14, v14, v15
	v_cvt_pk_bf16_f32 v15, v16, v17
	global_store_dwordx2 v[36:37], v[14:15], off offset:1536
	s_or_b64 exec, exec, s[36:37]
	v_cmp_gt_i32_e32 vcc, s4, v92
	s_and_saveexec_b64 s[36:37], vcc
	s_cbranch_execz .LBB0_442
.LBB0_480:
	v_mul_f32_e32 v0, v23, v23
	v_mul_f32_e32 v14, v11, v11
	v_fmac_f32_e32 v0, v22, v22
	v_fmac_f32_e32 v14, v10, v10
	v_fmac_f32_e32 v0, v24, v24
	v_fmac_f32_e32 v14, v12, v12
	v_fmac_f32_e32 v0, v25, v25
	v_fmac_f32_e32 v14, v13, v13
	v_add_f32_e32 v0, v14, v0
	v_mul_f32_e32 v14, v7, v7
	v_fmac_f32_e32 v14, v6, v6
	v_fmac_f32_e32 v14, v8, v8
	v_fmac_f32_e32 v14, v9, v9
	v_add_f32_e32 v0, v14, v0
	v_mul_f32_e32 v14, v3, v3
	v_fmac_f32_e32 v14, v2, v2
	v_fmac_f32_e32 v14, v4, v4
	v_fmac_f32_e32 v14, v5, v5
	v_add_f32_e32 v0, v14, v0
	v_min_i32_e32 v14, 0x8000, v92
	v_ashrrev_i32_e32 v14, 12, v14
	v_mul_i32_i24_e32 v14, 0x1800, v14
	v_ashrrev_i32_e32 v15, 31, v14
	v_lshl_add_u64 v[20:21], v[14:15], 2, s[22:23]
	ds_bpermute_b32 v14, v108, v0
	v_lshl_add_u64 v[18:19], v[20:21], 0, s[10:11]
	v_mov_b32_e32 v85, v1
	v_lshl_add_u64 v[26:27], v[18:19], 0, v[84:85]
	global_load_dwordx4 v[28:31], v[26:27], off
	s_waitcnt lgkmcnt(0)
	v_add_f32_e32 v0, v0, v14
	ds_bpermute_b32 v14, v109, v0
	v_lshl_add_u64 v[26:27], v[20:21], 0, v[84:85]
	global_load_dwordx4 v[32:35], v[26:27], off
	v_ashrrev_i32_e32 v93, 31, v92
	v_lshlrev_b64 v[36:37], 11, v[92:93]
	s_waitcnt lgkmcnt(0)
	v_add_f32_e32 v0, v0, v14
	ds_bpermute_b32 v14, v110, v0
	v_mov_b32_e32 v87, v1
	v_mov_b32_e32 v89, v1
	v_mov_b32_e32 v91, v1
	s_waitcnt lgkmcnt(0)
	v_add_f32_e32 v0, v0, v14
	ds_bpermute_b32 v14, v111, v0
	s_waitcnt lgkmcnt(0)
	v_add_f32_e32 v0, v0, v14
	ds_bpermute_b32 v14, v112, v0
	s_waitcnt lgkmcnt(0)
	v_add_f32_e32 v0, v0, v14
	ds_bpermute_b32 v14, v113, v0
	s_waitcnt lgkmcnt(0)
	v_add_f32_e32 v0, v0, v14
	v_fmamk_f32 v0, v0, 0x3a800000, v218
	v_cmp_gt_f32_e32 vcc, s13, v0
	v_mul_f32_e32 v14, 0x4b800000, v0
	s_nop 0
	v_cndmask_b32_e32 v0, v0, v14, vcc
	v_rsq_f32_e32 v0, v0
	s_nop 0
	v_mul_f32_e32 v14, 0x45800000, v0
	v_cndmask_b32_e32 v0, v0, v14, vcc
	global_load_dwordx4 v[14:17], v[76:77], off
	v_mov_b32_e32 v87, v1
	v_mov_b32_e32 v89, v1
	v_mov_b32_e32 v91, v1
	global_load_dwordx4 v[168:171], v[76:77], off offset:1024
	v_lshl_add_u64 v[172:173], v[18:19], 0, v[86:87]
	global_load_dwordx4 v[172:175], v[172:173], off
	global_load_dwordx4 v[176:179], v[26:27], off offset:1024
	global_load_dwordx4 v[180:183], v[76:77], off offset:2048
	v_lshl_add_u64 v[184:185], v[18:19], 0, v[88:89]
	global_load_dwordx4 v[184:187], v[184:185], off
	global_load_dwordx4 v[188:191], v[26:27], off offset:2048
	global_load_dwordx4 v[192:195], v[76:77], off offset:3072
	v_lshl_add_u64 v[196:197], v[18:19], 0, v[90:91]
	global_load_dwordx4 v[196:199], v[196:197], off
	global_load_dwordx4 v[200:203], v[26:27], off offset:3072
	v_pk_mul_f32 v[20:21], v[24:25], v[0:1] op_sel_hi:[1,0]
	v_pk_mul_f32 v[22:23], v[22:23], v[0:1] op_sel_hi:[1,0]
	v_pk_mul_f32 v[12:13], v[12:13], v[0:1] op_sel_hi:[1,0]
	v_pk_mul_f32 v[10:11], v[10:11], v[0:1] op_sel_hi:[1,0]
	v_pk_mul_f32 v[8:9], v[8:9], v[0:1] op_sel_hi:[1,0]
	v_pk_mul_f32 v[6:7], v[6:7], v[0:1] op_sel_hi:[1,0]
	v_pk_mul_f32 v[4:5], v[4:5], v[0:1] op_sel_hi:[1,0]
	v_pk_mul_f32 v[2:3], v[2:3], v[0:1] op_sel_hi:[1,0]
	s_waitcnt vmcnt(9)
	v_pk_mul_f32 v[14:15], v[14:15], v[22:23]
	v_pk_mul_f32 v[16:17], v[16:17], v[20:21]
	v_pk_add_f32 v[20:21], v[30:31], 1.0 op_sel_hi:[1,0]
	v_pk_add_f32 v[22:23], v[28:29], 1.0 op_sel_hi:[1,0]
	v_pk_fma_f32 v[16:17], v[20:21], v[16:17], v[34:35]
	v_pk_fma_f32 v[14:15], v[22:23], v[14:15], v[32:33]
	v_lshl_add_u64 v[20:21], v[80:81], 0, v[36:37]
	v_cvt_pk_bf16_f32 v14, v14, v15
	v_cvt_pk_bf16_f32 v15, v16, v17
	global_store_dwordx2 v[20:21], v[14:15], off
	v_lshl_add_u64 v[22:23], v[18:19], 0, v[86:87]
	s_waitcnt vmcnt(7)
	v_pk_mul_f32 v[10:11], v[168:169], v[10:11]
	v_pk_mul_f32 v[12:13], v[170:171], v[12:13]
	v_pk_add_f32 v[14:15], v[174:175], 1.0 op_sel_hi:[1, 0]
	v_pk_add_f32 v[16:17], v[172:173], 1.0 op_sel_hi:[1, 0]
	v_pk_fma_f32 v[12:13], v[14:15], v[12:13], v[178:179]
	v_pk_fma_f32 v[10:11], v[16:17], v[10:11], v[176:177]
	v_lshl_add_u64 v[14:15], v[18:19], 0, v[88:89]
	v_cvt_pk_bf16_f32 v10, v10, v11
	v_cvt_pk_bf16_f32 v11, v12, v13
	global_store_dwordx2 v[20:21], v[10:11], off offset:512
	s_waitcnt vmcnt(5)
	v_pk_mul_f32 v[6:7], v[180:181], v[6:7]
	v_pk_mul_f32 v[8:9], v[182:183], v[8:9]
	v_pk_add_f32 v[10:11], v[186:187], 1.0 op_sel_hi:[1, 0]
	v_pk_add_f32 v[12:13], v[184:185], 1.0 op_sel_hi:[1, 0]
	v_pk_fma_f32 v[8:9], v[10:11], v[8:9], v[190:191]
	v_pk_fma_f32 v[6:7], v[12:13], v[6:7], v[188:189]
	v_lshl_add_u64 v[10:11], v[18:19], 0, v[90:91]
	v_cvt_pk_bf16_f32 v6, v6, v7
	v_cvt_pk_bf16_f32 v7, v8, v9
	global_store_dwordx2 v[20:21], v[6:7], off offset:1024
	s_waitcnt vmcnt(3)
	v_pk_mul_f32 v[2:3], v[2:3], v[192:193]
	v_pk_mul_f32 v[4:5], v[4:5], v[194:195]
	v_pk_add_f32 v[6:7], v[198:199], 1.0 op_sel_hi:[1, 0]
	v_pk_add_f32 v[8:9], v[196:197], 1.0 op_sel_hi:[1, 0]
	v_pk_fma_f32 v[4:5], v[4:5], v[6:7], v[202:203]
	v_pk_fma_f32 v[2:3], v[2:3], v[8:9], v[200:201]
	s_nop 0
	v_cvt_pk_bf16_f32 v2, v2, v3
	v_cvt_pk_bf16_f32 v3, v4, v5
	global_store_dwordx2 v[20:21], v[2:3], off offset:1536
	s_branch .LBB0_442
	s_nop 0
	s_nop 0
	s_nop 0
	s_nop 0
	s_nop 0
	s_nop 0
	s_nop 0
	s_nop 0
	s_nop 0

.LBB0_562:
	s_or_b64 exec, exec, s[34:35]
	v_min_i32_e32 v0, 0x8000, v66
	v_ashrrev_i32_e32 v0, 12, v0
	v_mul_i32_i24_e32 v92, 0x1800, v0
	v_ashrrev_i32_e32 v93, 31, v92
	v_lshl_add_u64 v[100:101], v[92:93], 2, s[44:45]
	s_mov_b64 s[8:9], 0x1000
	v_lshl_add_u64 v[112:113], v[100:101], 0, s[8:9]
	v_mov_b32_e32 v79, v1
	v_lshl_add_u64 v[96:97], v[112:113], 0, v[78:79]
	global_load_dwordx4 v[92:95], v[70:71], off
	v_lshl_add_u64 v[100:101], v[100:101], 0, v[78:79]
	global_load_dwordx4 v[96:99], v[96:97], off
	s_waitcnt vmcnt(0)
	v_mul_f32_e32 v0, v39, v39
	global_load_dwordx4 v[108:111], v[100:101], off
	v_mov_b32_e32 v81, v1
	v_mov_b32_e32 v83, v1
	v_mov_b32_e32 v85, v1
	global_load_dwordx4 v[168:171], v[70:71], off offset:1024
	v_lshl_add_u64 v[172:173], v[112:113], 0, v[80:81]
	global_load_dwordx4 v[172:175], v[172:173], off
	global_load_dwordx4 v[176:179], v[100:101], off offset:1024
	global_load_dwordx4 v[180:183], v[70:71], off offset:2048
	v_lshl_add_u64 v[184:185], v[112:113], 0, v[82:83]
	global_load_dwordx4 v[184:187], v[184:185], off
	global_load_dwordx4 v[188:191], v[100:101], off offset:2048
	global_load_dwordx4 v[192:195], v[70:71], off offset:3072
	v_lshl_add_u64 v[196:197], v[112:113], 0, v[84:85]
	global_load_dwordx4 v[196:199], v[196:197], off
	global_load_dwordx4 v[200:203], v[100:101], off offset:3072
	v_mul_f32_e32 v81, v23, v23
	v_mul_f32_e32 v83, v7, v7
	v_fmac_f32_e32 v0, v38, v38
	v_fmac_f32_e32 v81, v22, v22
	v_mul_f32_e32 v85, v3, v3
	v_fmac_f32_e32 v83, v6, v6
	v_fmac_f32_e32 v0, v40, v40
	v_fmac_f32_e32 v81, v24, v24
	v_fmac_f32_e32 v85, v2, v2
	v_fmac_f32_e32 v83, v8, v8
	v_fmac_f32_e32 v0, v41, v41
	v_fmac_f32_e32 v81, v25, v25
	v_fmac_f32_e32 v85, v4, v4
	v_fmac_f32_e32 v83, v9, v9
	v_add_f32_e32 v0, v81, v0
	v_fmac_f32_e32 v85, v5, v5
	v_add_f32_e32 v0, v83, v0
	v_add_f32_e32 v0, v85, v0
	ds_bpermute_b32 v81, v102, v0
	v_mov_b32_e32 v85, v1
	s_waitcnt lgkmcnt(0)
	v_add_f32_e32 v0, v0, v81
	ds_bpermute_b32 v81, v103, v0
	s_waitcnt lgkmcnt(0)
	v_add_f32_e32 v0, v0, v81
	ds_bpermute_b32 v81, v104, v0
	s_waitcnt lgkmcnt(0)
	v_add_f32_e32 v0, v0, v81
	ds_bpermute_b32 v81, v105, v0
	s_waitcnt lgkmcnt(0)
	v_add_f32_e32 v0, v0, v81
	ds_bpermute_b32 v81, v106, v0
	s_waitcnt lgkmcnt(0)
	v_add_f32_e32 v0, v0, v81
	ds_bpermute_b32 v81, v107, v0
	s_waitcnt lgkmcnt(0)
	v_add_f32_e32 v0, v0, v81
	v_fmamk_f32 v0, v0, 0x3a800000, v218
	v_mul_f32_e32 v81, 0x4b800000, v0
	v_cmp_gt_f32_e32 vcc, s13, v0
	s_nop 1
	v_cndmask_b32_e32 v0, v0, v81, vcc
	v_rsq_f32_e32 v0, v0
	v_mov_b32_e32 v81, v1
	v_mul_f32_e32 v83, 0x45800000, v0
	v_cndmask_b32_e32 v0, v0, v83, vcc
	v_pk_mul_f32 v[40:41], v[40:41], v[0:1] op_sel_hi:[1,0]
	v_pk_mul_f32 v[38:39], v[38:39], v[0:1] op_sel_hi:[1,0]
	v_pk_mul_f32 v[24:25], v[24:25], v[0:1] op_sel_hi:[1,0]
	v_pk_mul_f32 v[22:23], v[22:23], v[0:1] op_sel_hi:[1,0]
	v_mov_b32_e32 v83, v1
	v_pk_mul_f32 v[8:9], v[8:9], v[0:1] op_sel_hi:[1,0]
	v_pk_mul_f32 v[6:7], v[6:7], v[0:1] op_sel_hi:[1,0]
	v_pk_mul_f32 v[4:5], v[4:5], v[0:1] op_sel_hi:[1,0]
	v_pk_mul_f32 v[2:3], v[2:3], v[0:1] op_sel_hi:[1,0]
	v_pk_mul_f32 v[38:39], v[92:93], v[38:39]
	v_pk_mul_f32 v[40:41], v[94:95], v[40:41]
	v_pk_add_f32 v[92:93], v[98:99], 1.0 op_sel_hi:[1,0]
	v_pk_add_f32 v[94:95], v[96:97], 1.0 op_sel_hi:[1,0]
	s_waitcnt vmcnt(9)
	v_pk_fma_f32 v[40:41], v[92:93], v[40:41], v[110:111]
	v_pk_fma_f32 v[38:39], v[94:95], v[38:39], v[108:109]
	v_lshl_add_u64 v[92:93], v[112:113], 0, v[80:81]
	v_cvt_pk_bf16_f32 v38, v38, v39
	v_cvt_pk_bf16_f32 v39, v40, v41
	global_store_dwordx2 v[76:77], v[38:39], off
	v_cmp_gt_i32_e32 vcc, s15, v86
	s_waitcnt vmcnt(7)
	v_pk_mul_f32 v[22:23], v[168:169], v[22:23]
	v_pk_mul_f32 v[24:25], v[170:171], v[24:25]
	v_pk_add_f32 v[38:39], v[174:175], 1.0 op_sel_hi:[1, 0]
	v_pk_add_f32 v[40:41], v[172:173], 1.0 op_sel_hi:[1, 0]
	v_pk_fma_f32 v[24:25], v[38:39], v[24:25], v[178:179]
	v_pk_fma_f32 v[22:23], v[40:41], v[22:23], v[176:177]
	v_lshl_add_u64 v[38:39], v[112:113], 0, v[82:83]
	v_cvt_pk_bf16_f32 v22, v22, v23
	v_cvt_pk_bf16_f32 v23, v24, v25
	global_store_dwordx2 v[76:77], v[22:23], off offset:512
	s_waitcnt vmcnt(5)
	v_pk_mul_f32 v[6:7], v[180:181], v[6:7]
	v_pk_mul_f32 v[8:9], v[182:183], v[8:9]
	v_pk_add_f32 v[22:23], v[186:187], 1.0 op_sel_hi:[1, 0]
	v_pk_add_f32 v[24:25], v[184:185], 1.0 op_sel_hi:[1, 0]
	v_pk_fma_f32 v[8:9], v[22:23], v[8:9], v[190:191]
	v_pk_fma_f32 v[6:7], v[24:25], v[6:7], v[188:189]
	v_lshl_add_u64 v[22:23], v[112:113], 0, v[84:85]
	v_cvt_pk_bf16_f32 v6, v6, v7
	v_cvt_pk_bf16_f32 v7, v8, v9
	global_store_dwordx2 v[76:77], v[6:7], off offset:1024
	s_waitcnt vmcnt(3)
	v_pk_mul_f32 v[2:3], v[2:3], v[192:193]
	v_pk_mul_f32 v[4:5], v[4:5], v[194:195]
	v_pk_add_f32 v[6:7], v[198:199], 1.0 op_sel_hi:[1, 0]
	v_pk_add_f32 v[8:9], v[196:197], 1.0 op_sel_hi:[1, 0]
	v_pk_fma_f32 v[4:5], v[4:5], v[6:7], v[202:203]
	v_pk_fma_f32 v[2:3], v[2:3], v[8:9], v[200:201]
	s_nop 0
	v_cvt_pk_bf16_f32 v2, v2, v3
	v_cvt_pk_bf16_f32 v3, v4, v5
	global_store_dwordx2 v[76:77], v[2:3], off offset:1536
	s_and_saveexec_b64 s[34:35], vcc
	s_cbranch_execz .LBB0_565
	v_min_i32_e32 v0, 0x8000, v86
	v_ashrrev_i32_e32 v0, 12, v0
	v_mul_i32_i24_e32 v2, 0x1800, v0
	v_ashrrev_i32_e32 v3, 31, v2
	v_lshl_add_u64 v[22:23], v[2:3], 2, s[44:45]
	v_lshl_add_u64 v[38:39], v[22:23], 0, s[8:9]
	v_lshl_add_u64 v[6:7], v[38:39], 0, v[78:79]
	global_load_dwordx4 v[2:5], v[70:71], off
	v_lshl_add_u64 v[40:41], v[22:23], 0, v[78:79]
	global_load_dwordx4 v[6:9], v[6:7], off
	v_mul_f32_e32 v0, v35, v35
	global_load_dwordx4 v[22:25], v[40:41], off
	v_mov_b32_e32 v81, v1
	v_mov_b32_e32 v83, v1
	v_mov_b32_e32 v85, v1
	global_load_dwordx4 v[168:171], v[70:71], off offset:1024
	v_lshl_add_u64 v[172:173], v[38:39], 0, v[80:81]
	global_load_dwordx4 v[172:175], v[172:173], off
	global_load_dwordx4 v[176:179], v[40:41], off offset:1024
	global_load_dwordx4 v[180:183], v[70:71], off offset:2048
	v_lshl_add_u64 v[184:185], v[38:39], 0, v[82:83]
	global_load_dwordx4 v[184:187], v[184:185], off
	global_load_dwordx4 v[188:191], v[40:41], off offset:2048
	global_load_dwordx4 v[192:195], v[70:71], off offset:3072
	v_lshl_add_u64 v[196:197], v[38:39], 0, v[84:85]
	global_load_dwordx4 v[196:199], v[196:197], off
	global_load_dwordx4 v[200:203], v[40:41], off offset:3072
	v_mul_f32_e32 v79, v31, v31
	v_mul_f32_e32 v87, v19, v19
	v_fmac_f32_e32 v0, v34, v34
	v_fmac_f32_e32 v79, v30, v30
	v_mul_f32_e32 v89, v11, v11
	v_fmac_f32_e32 v87, v18, v18
	v_fmac_f32_e32 v0, v36, v36
	v_fmac_f32_e32 v79, v32, v32
	v_fmac_f32_e32 v89, v10, v10
	v_fmac_f32_e32 v87, v20, v20
	v_fmac_f32_e32 v0, v37, v37
	v_fmac_f32_e32 v79, v33, v33
	v_fmac_f32_e32 v89, v12, v12
	v_fmac_f32_e32 v87, v21, v21
	v_add_f32_e32 v0, v79, v0
	v_fmac_f32_e32 v89, v13, v13
	v_add_f32_e32 v0, v87, v0
	v_add_f32_e32 v0, v89, v0
	ds_bpermute_b32 v79, v102, v0
	v_ashrrev_i32_e32 v87, 31, v86
	v_lshlrev_b64 v[86:87], 11, v[86:87]
	v_lshl_add_u64 v[86:87], v[74:75], 0, v[86:87]
	s_waitcnt lgkmcnt(0)
	v_add_f32_e32 v0, v0, v79
	ds_bpermute_b32 v79, v103, v0
	s_waitcnt lgkmcnt(0)
	v_add_f32_e32 v0, v0, v79
	ds_bpermute_b32 v79, v104, v0
	s_waitcnt lgkmcnt(0)
	v_add_f32_e32 v0, v0, v79
	ds_bpermute_b32 v79, v105, v0
	s_waitcnt lgkmcnt(0)
	v_add_f32_e32 v0, v0, v79
	ds_bpermute_b32 v79, v106, v0
	s_waitcnt lgkmcnt(0)
	v_add_f32_e32 v0, v0, v79
	ds_bpermute_b32 v79, v107, v0
	s_waitcnt lgkmcnt(0)
	v_add_f32_e32 v0, v0, v79
	v_fmamk_f32 v0, v0, 0x3a800000, v218
	v_mul_f32_e32 v79, 0x4b800000, v0
	v_cmp_gt_f32_e32 vcc, s13, v0
	s_waitcnt vmcnt(10)
	v_pk_add_f32 v[8:9], v[8:9], 1.0 op_sel_hi:[1,0]
	v_cndmask_b32_e32 v0, v0, v79, vcc
	v_rsq_f32_e32 v0, v0
	v_pk_add_f32 v[6:7], v[6:7], 1.0 op_sel_hi:[1,0]
	v_mul_f32_e32 v79, 0x45800000, v0
	v_cndmask_b32_e32 v0, v0, v79, vcc
	v_pk_mul_f32 v[36:37], v[36:37], v[0:1] op_sel_hi:[1,0]
	v_pk_mul_f32 v[34:35], v[34:35], v[0:1] op_sel_hi:[1,0]
	v_pk_mul_f32 v[4:5], v[4:5], v[36:37]
	v_pk_mul_f32 v[2:3], v[2:3], v[34:35]
	s_waitcnt vmcnt(9)
	v_pk_fma_f32 v[4:5], v[8:9], v[4:5], v[24:25]
	v_pk_fma_f32 v[2:3], v[6:7], v[2:3], v[22:23]
	v_lshl_add_u64 v[6:7], v[38:39], 0, v[80:81]
	v_cvt_pk_bf16_f32 v2, v2, v3
	v_cvt_pk_bf16_f32 v3, v4, v5
	global_store_dwordx2 v[86:87], v[2:3], off
	v_pk_mul_f32 v[32:33], v[32:33], v[0:1] op_sel_hi:[1,0]
	v_pk_mul_f32 v[30:31], v[30:31], v[0:1] op_sel_hi:[1,0]
	v_pk_mul_f32 v[20:21], v[20:21], v[0:1] op_sel_hi:[1,0]
	v_pk_mul_f32 v[18:19], v[18:19], v[0:1] op_sel_hi:[1,0]
	v_pk_mul_f32 v[12:13], v[12:13], v[0:1] op_sel_hi:[1,0]
	v_pk_mul_f32 v[10:11], v[10:11], v[0:1] op_sel_hi:[1,0]
	s_waitcnt vmcnt(7)
	v_pk_add_f32 v[8:9], v[174:175], 1.0 op_sel_hi:[1, 0]
	v_pk_mul_f32 v[2:3], v[168:169], v[30:31]
	v_pk_mul_f32 v[4:5], v[170:171], v[32:33]
	v_pk_add_f32 v[6:7], v[172:173], 1.0 op_sel_hi:[1, 0]
	v_pk_fma_f32 v[4:5], v[8:9], v[4:5], v[178:179]
	v_pk_fma_f32 v[2:3], v[6:7], v[2:3], v[176:177]
	v_lshl_add_u64 v[6:7], v[38:39], 0, v[82:83]
	v_cvt_pk_bf16_f32 v2, v2, v3
	v_cvt_pk_bf16_f32 v3, v4, v5
	global_store_dwordx2 v[86:87], v[2:3], off offset:512
	s_waitcnt vmcnt(5)
	v_pk_add_f32 v[8:9], v[186:187], 1.0 op_sel_hi:[1, 0]
	v_pk_mul_f32 v[2:3], v[180:181], v[18:19]
	v_pk_mul_f32 v[4:5], v[182:183], v[20:21]
	v_pk_add_f32 v[6:7], v[184:185], 1.0 op_sel_hi:[1, 0]
	v_pk_fma_f32 v[4:5], v[8:9], v[4:5], v[190:191]
	v_pk_fma_f32 v[2:3], v[6:7], v[2:3], v[188:189]
	v_lshl_add_u64 v[6:7], v[38:39], 0, v[84:85]
	v_cvt_pk_bf16_f32 v2, v2, v3
	v_cvt_pk_bf16_f32 v3, v4, v5
	global_store_dwordx2 v[86:87], v[2:3], off offset:1024
	s_waitcnt vmcnt(3)
	v_pk_add_f32 v[8:9], v[198:199], 1.0 op_sel_hi:[1, 0]
	v_pk_mul_f32 v[2:3], v[10:11], v[192:193]
	v_pk_mul_f32 v[4:5], v[12:13], v[194:195]
	v_pk_add_f32 v[6:7], v[196:197], 1.0 op_sel_hi:[1, 0]
	v_pk_fma_f32 v[4:5], v[4:5], v[8:9], v[202:203]
	v_pk_fma_f32 v[2:3], v[2:3], v[6:7], v[200:201]
	s_nop 0
	v_cvt_pk_bf16_f32 v2, v2, v3
	v_cvt_pk_bf16_f32 v3, v4, v5
	global_store_dwordx2 v[86:87], v[2:3], off offset:1536
	s_or_b64 exec, exec, s[34:35]
	v_cmp_gt_i32_e32 vcc, s15, v88
	s_and_saveexec_b64 s[34:35], vcc
	s_cbranch_execnz .LBB0_566

.LBB0_566:
	v_min_i32_e32 v0, 0x8000, v88
	v_ashrrev_i32_e32 v0, 12, v0
	v_mul_i32_i24_e32 v2, 0x1800, v0
	v_ashrrev_i32_e32 v3, 31, v2
	v_lshl_add_u64 v[10:11], v[2:3], 2, s[44:45]
	v_lshl_add_u64 v[18:19], v[10:11], 0, s[8:9]
	v_mov_b32_e32 v79, v1
	v_lshl_add_u64 v[6:7], v[18:19], 0, v[78:79]
	global_load_dwordx4 v[2:5], v[70:71], off
	v_lshl_add_u64 v[20:21], v[10:11], 0, v[78:79]
	global_load_dwordx4 v[6:9], v[6:7], off
	v_mul_f32_e32 v0, v47, v47
	global_load_dwordx4 v[10:13], v[20:21], off
	v_mov_b32_e32 v81, v1
	v_mov_b32_e32 v83, v1
	v_mov_b32_e32 v85, v1
	global_load_dwordx4 v[168:171], v[70:71], off offset:1024
	v_lshl_add_u64 v[172:173], v[18:19], 0, v[80:81]
	global_load_dwordx4 v[172:175], v[172:173], off
	global_load_dwordx4 v[176:179], v[20:21], off offset:1024
	global_load_dwordx4 v[180:183], v[70:71], off offset:2048
	v_lshl_add_u64 v[184:185], v[18:19], 0, v[82:83]
	global_load_dwordx4 v[184:187], v[184:185], off
	global_load_dwordx4 v[188:191], v[20:21], off offset:2048
	global_load_dwordx4 v[192:195], v[70:71], off offset:3072
	v_lshl_add_u64 v[196:197], v[18:19], 0, v[84:85]
	global_load_dwordx4 v[196:199], v[196:197], off
	global_load_dwordx4 v[200:203], v[20:21], off offset:3072
	v_mul_f32_e32 v22, v43, v43
	v_mul_f32_e32 v23, v27, v27
	v_fmac_f32_e32 v0, v46, v46
	v_fmac_f32_e32 v22, v42, v42
	v_mul_f32_e32 v24, v15, v15
	v_fmac_f32_e32 v23, v26, v26
	v_fmac_f32_e32 v0, v48, v48
	v_fmac_f32_e32 v22, v44, v44
	v_fmac_f32_e32 v24, v14, v14
	v_fmac_f32_e32 v23, v28, v28
	v_fmac_f32_e32 v0, v49, v49
	v_fmac_f32_e32 v22, v45, v45
	v_fmac_f32_e32 v24, v16, v16
	v_fmac_f32_e32 v23, v29, v29
	v_add_f32_e32 v0, v22, v0
	v_fmac_f32_e32 v24, v17, v17
	v_add_f32_e32 v0, v23, v0
	v_add_f32_e32 v0, v24, v0
	ds_bpermute_b32 v22, v102, v0
	v_ashrrev_i32_e32 v89, 31, v88
	v_mov_b32_e32 v81, v1
	v_mov_b32_e32 v83, v1
	v_mov_b32_e32 v85, v1
	s_waitcnt lgkmcnt(0)
	v_add_f32_e32 v0, v0, v22
	ds_bpermute_b32 v22, v103, v0
	s_waitcnt lgkmcnt(0)
	v_add_f32_e32 v0, v0, v22
	ds_bpermute_b32 v22, v104, v0
	s_waitcnt lgkmcnt(0)
	v_add_f32_e32 v0, v0, v22
	ds_bpermute_b32 v22, v105, v0
	s_waitcnt lgkmcnt(0)
	v_add_f32_e32 v0, v0, v22
	ds_bpermute_b32 v22, v106, v0
	s_waitcnt lgkmcnt(0)
	v_add_f32_e32 v0, v0, v22
	ds_bpermute_b32 v22, v107, v0
	s_waitcnt lgkmcnt(0)
	v_add_f32_e32 v0, v0, v22
	v_fmamk_f32 v0, v0, 0x3a800000, v218
	v_mul_f32_e32 v22, 0x4b800000, v0
	v_cmp_gt_f32_e32 vcc, s13, v0
	s_waitcnt vmcnt(10)
	v_pk_add_f32 v[8:9], v[8:9], 1.0 op_sel_hi:[1,0]
	v_cndmask_b32_e32 v0, v0, v22, vcc
	v_rsq_f32_e32 v0, v0
	v_pk_add_f32 v[6:7], v[6:7], 1.0 op_sel_hi:[1,0]
	v_lshlrev_b64 v[22:23], 11, v[88:89]
	v_lshl_add_u64 v[22:23], v[74:75], 0, v[22:23]
	v_mul_f32_e32 v24, 0x45800000, v0
	v_cndmask_b32_e32 v0, v0, v24, vcc
	v_pk_mul_f32 v[24:25], v[48:49], v[0:1] op_sel_hi:[1,0]
	v_pk_mul_f32 v[30:31], v[46:47], v[0:1] op_sel_hi:[1,0]
	v_pk_mul_f32 v[4:5], v[4:5], v[24:25]
	v_pk_mul_f32 v[2:3], v[2:3], v[30:31]
	s_waitcnt vmcnt(9)
	v_pk_fma_f32 v[4:5], v[8:9], v[4:5], v[12:13]
	v_pk_fma_f32 v[2:3], v[6:7], v[2:3], v[10:11]
	v_lshl_add_u64 v[6:7], v[18:19], 0, v[80:81]
	v_cvt_pk_bf16_f32 v2, v2, v3
	v_cvt_pk_bf16_f32 v3, v4, v5
	global_store_dwordx2 v[22:23], v[2:3], off
	v_pk_mul_f32 v[24:25], v[44:45], v[0:1] op_sel_hi:[1,0]
	v_pk_mul_f32 v[30:31], v[42:43], v[0:1] op_sel_hi:[1,0]
	v_pk_mul_f32 v[26:27], v[26:27], v[0:1] op_sel_hi:[1,0]
	v_pk_mul_f32 v[16:17], v[16:17], v[0:1] op_sel_hi:[1,0]
	v_pk_mul_f32 v[14:15], v[14:15], v[0:1] op_sel_hi:[1,0]
	s_waitcnt vmcnt(7)
	v_pk_add_f32 v[8:9], v[174:175], 1.0 op_sel_hi:[1, 0]
	v_pk_mul_f32 v[2:3], v[168:169], v[30:31]
	v_pk_mul_f32 v[4:5], v[170:171], v[24:25]
	v_pk_add_f32 v[6:7], v[172:173], 1.0 op_sel_hi:[1, 0]
	v_pk_fma_f32 v[4:5], v[8:9], v[4:5], v[178:179]
	v_pk_fma_f32 v[2:3], v[6:7], v[2:3], v[176:177]
	v_lshl_add_u64 v[6:7], v[18:19], 0, v[82:83]
	v_cvt_pk_bf16_f32 v2, v2, v3
	v_cvt_pk_bf16_f32 v3, v4, v5
	global_store_dwordx2 v[22:23], v[2:3], off offset:512
	v_pk_mul_f32 v[24:25], v[28:29], v[0:1] op_sel_hi:[1,0]
	s_waitcnt vmcnt(5)
	v_pk_add_f32 v[8:9], v[186:187], 1.0 op_sel_hi:[1, 0]
	v_pk_mul_f32 v[2:3], v[180:181], v[26:27]
	v_pk_mul_f32 v[4:5], v[182:183], v[24:25]
	v_pk_add_f32 v[6:7], v[184:185], 1.0 op_sel_hi:[1, 0]
	v_pk_fma_f32 v[4:5], v[8:9], v[4:5], v[190:191]
	v_pk_fma_f32 v[2:3], v[6:7], v[2:3], v[188:189]
	v_lshl_add_u64 v[6:7], v[18:19], 0, v[84:85]
	v_cvt_pk_bf16_f32 v2, v2, v3
	v_cvt_pk_bf16_f32 v3, v4, v5
	global_store_dwordx2 v[22:23], v[2:3], off offset:1024
	s_waitcnt vmcnt(3)
	v_pk_add_f32 v[8:9], v[198:199], 1.0 op_sel_hi:[1, 0]
	v_pk_mul_f32 v[2:3], v[14:15], v[192:193]
	v_pk_mul_f32 v[4:5], v[16:17], v[194:195]
	v_pk_add_f32 v[6:7], v[196:197], 1.0 op_sel_hi:[1, 0]
	v_pk_fma_f32 v[4:5], v[4:5], v[8:9], v[202:203]
	v_pk_fma_f32 v[2:3], v[2:3], v[6:7], v[200:201]
	s_nop 0
	v_cvt_pk_bf16_f32 v2, v2, v3
	v_cvt_pk_bf16_f32 v3, v4, v5
	global_store_dwordx2 v[22:23], v[2:3], off offset:1536
	s_or_b64 exec, exec, s[34:35]
	v_cmp_gt_i32_e32 vcc, s15, v90
	s_and_saveexec_b64 s[34:35], vcc
	s_cbranch_execz .LBB0_529
.LBB0_567:
	v_min_i32_e32 v0, 0x8000, v90
	v_ashrrev_i32_e32 v0, 12, v0
	v_mul_i32_i24_e32 v2, 0x1800, v0
	v_ashrrev_i32_e32 v3, 31, v2
	v_lshl_add_u64 v[10:11], v[2:3], 2, s[44:45]
	v_lshl_add_u64 v[14:15], v[10:11], 0, s[8:9]
	v_mov_b32_e32 v79, v1
	v_lshl_add_u64 v[6:7], v[14:15], 0, v[78:79]
	global_load_dwordx4 v[2:5], v[70:71], off
	v_lshl_add_u64 v[16:17], v[10:11], 0, v[78:79]
	global_load_dwordx4 v[6:9], v[6:7], off
	v_mul_f32_e32 v0, v63, v63
	global_load_dwordx4 v[10:13], v[16:17], off
	v_mov_b32_e32 v81, v1
	v_mov_b32_e32 v83, v1
	v_mov_b32_e32 v85, v1
	global_load_dwordx4 v[168:171], v[70:71], off offset:1024
	v_lshl_add_u64 v[172:173], v[14:15], 0, v[80:81]
	global_load_dwordx4 v[172:175], v[172:173], off
	global_load_dwordx4 v[176:179], v[16:17], off offset:1024
	global_load_dwordx4 v[180:183], v[70:71], off offset:2048
	v_lshl_add_u64 v[184:185], v[14:15], 0, v[82:83]
	global_load_dwordx4 v[184:187], v[184:185], off
	global_load_dwordx4 v[188:191], v[16:17], off offset:2048
	global_load_dwordx4 v[192:195], v[70:71], off offset:3072
	v_lshl_add_u64 v[196:197], v[14:15], 0, v[84:85]
	global_load_dwordx4 v[196:199], v[196:197], off
	global_load_dwordx4 v[200:203], v[16:17], off offset:3072
	v_mul_f32_e32 v18, v59, v59
	v_mul_f32_e32 v19, v55, v55
	v_fmac_f32_e32 v0, v62, v62
	v_fmac_f32_e32 v18, v58, v58
	v_mul_f32_e32 v20, v51, v51
	v_fmac_f32_e32 v19, v54, v54
	v_fmac_f32_e32 v0, v64, v64
	v_fmac_f32_e32 v18, v60, v60
	v_fmac_f32_e32 v20, v50, v50
	v_fmac_f32_e32 v19, v56, v56
	v_fmac_f32_e32 v0, v65, v65
	v_fmac_f32_e32 v18, v61, v61
	v_fmac_f32_e32 v20, v52, v52
	v_fmac_f32_e32 v19, v57, v57
	v_add_f32_e32 v0, v18, v0
	v_fmac_f32_e32 v20, v53, v53
	v_add_f32_e32 v0, v19, v0
	v_add_f32_e32 v0, v20, v0
	ds_bpermute_b32 v18, v102, v0
	v_ashrrev_i32_e32 v91, 31, v90
	v_mov_b32_e32 v81, v1
	v_mov_b32_e32 v83, v1
	v_mov_b32_e32 v85, v1
	s_waitcnt lgkmcnt(0)
	v_add_f32_e32 v0, v0, v18
	ds_bpermute_b32 v18, v103, v0
	s_waitcnt lgkmcnt(0)
	v_add_f32_e32 v0, v0, v18
	ds_bpermute_b32 v18, v104, v0
	s_waitcnt lgkmcnt(0)
	v_add_f32_e32 v0, v0, v18
	ds_bpermute_b32 v18, v105, v0
	s_waitcnt lgkmcnt(0)
	v_add_f32_e32 v0, v0, v18
	ds_bpermute_b32 v18, v106, v0
	s_waitcnt lgkmcnt(0)
	v_add_f32_e32 v0, v0, v18
	ds_bpermute_b32 v18, v107, v0
	s_waitcnt lgkmcnt(0)
	v_add_f32_e32 v0, v0, v18
	v_fmamk_f32 v0, v0, 0x3a800000, v218
	v_mul_f32_e32 v18, 0x4b800000, v0
	v_cmp_gt_f32_e32 vcc, s13, v0
	s_waitcnt vmcnt(10)
	v_pk_add_f32 v[8:9], v[8:9], 1.0 op_sel_hi:[1,0]
	v_cndmask_b32_e32 v0, v0, v18, vcc
	v_rsq_f32_e32 v0, v0
	v_pk_add_f32 v[6:7], v[6:7], 1.0 op_sel_hi:[1,0]
	v_lshlrev_b64 v[18:19], 11, v[90:91]
	v_lshl_add_u64 v[18:19], v[74:75], 0, v[18:19]
	v_mul_f32_e32 v20, 0x45800000, v0
	v_cndmask_b32_e32 v0, v0, v20, vcc
	v_pk_mul_f32 v[20:21], v[64:65], v[0:1] op_sel_hi:[1,0]
	v_pk_mul_f32 v[22:23], v[62:63], v[0:1] op_sel_hi:[1,0]
	v_pk_mul_f32 v[4:5], v[4:5], v[20:21]
	v_pk_mul_f32 v[2:3], v[2:3], v[22:23]
	s_waitcnt vmcnt(9)
	v_pk_fma_f32 v[4:5], v[8:9], v[4:5], v[12:13]
	v_pk_fma_f32 v[2:3], v[6:7], v[2:3], v[10:11]
	v_lshl_add_u64 v[6:7], v[14:15], 0, v[80:81]
	v_cvt_pk_bf16_f32 v2, v2, v3
	v_cvt_pk_bf16_f32 v3, v4, v5
	global_store_dwordx2 v[18:19], v[2:3], off
	v_pk_mul_f32 v[20:21], v[60:61], v[0:1] op_sel_hi:[1,0]
	v_pk_mul_f32 v[22:23], v[58:59], v[0:1] op_sel_hi:[1,0]
	s_waitcnt vmcnt(7)
	v_pk_add_f32 v[8:9], v[174:175], 1.0 op_sel_hi:[1, 0]
	v_pk_mul_f32 v[2:3], v[168:169], v[22:23]
	v_pk_mul_f32 v[4:5], v[170:171], v[20:21]
	v_pk_add_f32 v[6:7], v[172:173], 1.0 op_sel_hi:[1, 0]
	v_pk_fma_f32 v[4:5], v[8:9], v[4:5], v[178:179]
	v_pk_fma_f32 v[2:3], v[6:7], v[2:3], v[176:177]
	v_lshl_add_u64 v[6:7], v[14:15], 0, v[82:83]
	v_cvt_pk_bf16_f32 v2, v2, v3
	v_cvt_pk_bf16_f32 v3, v4, v5
	global_store_dwordx2 v[18:19], v[2:3], off offset:512
	v_pk_mul_f32 v[20:21], v[56:57], v[0:1] op_sel_hi:[1,0]
	v_pk_mul_f32 v[22:23], v[54:55], v[0:1] op_sel_hi:[1,0]
	s_waitcnt vmcnt(5)
	v_pk_add_f32 v[8:9], v[186:187], 1.0 op_sel_hi:[1, 0]
	v_pk_mul_f32 v[2:3], v[180:181], v[22:23]
	v_pk_mul_f32 v[4:5], v[182:183], v[20:21]
	v_pk_add_f32 v[6:7], v[184:185], 1.0 op_sel_hi:[1, 0]
	v_pk_fma_f32 v[4:5], v[8:9], v[4:5], v[190:191]
	v_pk_fma_f32 v[2:3], v[6:7], v[2:3], v[188:189]
	v_lshl_add_u64 v[6:7], v[14:15], 0, v[84:85]
	v_cvt_pk_bf16_f32 v2, v2, v3
	v_cvt_pk_bf16_f32 v3, v4, v5
	global_store_dwordx2 v[18:19], v[2:3], off offset:1024
	v_pk_mul_f32 v[14:15], v[52:53], v[0:1] op_sel_hi:[1,0]
	v_pk_mul_f32 v[16:17], v[50:51], v[0:1] op_sel_hi:[1,0]
	s_waitcnt vmcnt(3)
	v_pk_add_f32 v[8:9], v[198:199], 1.0 op_sel_hi:[1, 0]
	v_pk_mul_f32 v[2:3], v[16:17], v[192:193]
	v_pk_mul_f32 v[4:5], v[14:15], v[194:195]
	v_pk_add_f32 v[6:7], v[196:197], 1.0 op_sel_hi:[1, 0]
	v_pk_fma_f32 v[4:5], v[4:5], v[8:9], v[202:203]
	v_pk_fma_f32 v[2:3], v[2:3], v[6:7], v[200:201]
	s_nop 0
	v_cvt_pk_bf16_f32 v2, v2, v3
	v_cvt_pk_bf16_f32 v3, v4, v5
	global_store_dwordx2 v[18:19], v[2:3], off offset:1536
	s_branch .LBB0_529
	s_nop 0
	s_nop 0
	s_nop 0
